# XCD-local barrier: no-return arrival + poll of the arrival counter against a tracked target (one L2 round trip less), on v38
# baseline (speedup 1.0000x reference)
_Z6mk_fwd4Args:
	s_load_dwordx4 s[76:79], s[0:1], 0x120
	s_load_dwordx2 s[74:75], s[0:1], 0x138
	s_load_dword s38, s[0:1], 0x140
	v_and_b32_e32 v155, 0x3ff, v0
	s_add_u32 s4, s0, 0x138
	v_writelane_b32 v254, s2, 0
	v_writelane_b32 v255, 0, 60
	s_addc_u32 s5, s1, 0
	v_cmp_gt_u32_e32 vcc, 8, v155
	s_and_saveexec_b64 s[2:3], vcc
	v_lshl_add_u32 v1, v155, 2, 0
	v_add_u32_e32 v1, 0x21000, v1
	v_mov_b32_e32 v2, 0
	ds_write_b32 v1, v2
	s_or_b64 exec, exec, s[2:3]
	s_load_dwordx2 s[2:3], s[0:1], 0x130
	s_waitcnt lgkmcnt(0)
	s_barrier
	v_cmp_eq_u32_e64 s[6:7], 0, v155
	v_writelane_b32 v254, s2, 1
	s_nop 1
	v_writelane_b32 v254, s3, 2
	s_getreg_b32 s2, hwreg(HW_REG_XCC_ID, 0, 4)
	s_and_b32 s33, s2, 15
	s_mov_b64 s[2:3], exec
	v_writelane_b32 v254, s6, 3
	s_nop 1
	v_writelane_b32 v254, s7, 4
	s_and_b64 s[6:7], s[2:3], s[6:7]
	s_mov_b64 exec, s[6:7]
	s_cbranch_execz .LBB0_6
	s_mov_b64 s[8:9], exec
	v_mbcnt_lo_u32_b32 v1, s8, 0
	v_mbcnt_hi_u32_b32 v1, s9, v1
	v_cmp_eq_u32_e32 vcc, 0, v1
	s_and_saveexec_b64 s[6:7], vcc
	s_cbranch_execz .LBB0_5
	s_lshl_b32 s10, s33, 8
	s_bcnt1_i32_b64 s8, s[8:9]
	v_mov_b32_e32 v2, s10
	v_mov_b32_e32 v3, s8
	global_atomic_add v2, v2, v3, s[78:79] offset:1024 sc0

.LBB0_426:
	s_and_b64 vcc, exec, s[38:39]
	s_cbranch_vccz .LBB0_446
	s_waitcnt vmcnt(0)
	s_barrier
	s_mov_b64 s[38:39], exec
	v_readlane_b32 s20, v254, 3
	v_readlane_b32 s21, v254, 4
	s_and_b64 s[20:21], s[38:39], s[20:21]
	s_mov_b64 exec, s[20:21]
	s_cbranch_execz .LBB0_445
	buffer_inv sc1
	v_readlane_b32 s20, v254, 61
	v_readlane_b32 s21, v254, 62
	v_readlane_b32 s6, v255, 60
	v_mov_b32_e32 v0, 1
	s_nop 3
	s_add_i32 s6, s6, 32
	global_atomic_add v49, v0, s[20:21]
	v_writelane_b32 v255, s6, 60
.Llb_poll0:
	global_load_dword v1, v49, s[20:21] sc1
	s_waitcnt vmcnt(0)
	v_readfirstlane_b32 s26, v1
	s_nop 0
	s_cmp_ge_u32 s26, s6
	s_cbranch_scc1 .Llb_done0
	s_sleep 1
	s_branch .Llb_poll0
.Llb_done0:
.LBB0_445:
	s_or_b64 exec, exec, s[38:39]
	s_barrier

.LBB0_752:
	s_and_b64 vcc, exec, s[40:41]
	s_cbranch_vccz .LBB0_772
	s_waitcnt vmcnt(0)
	s_barrier
	s_mov_b64 s[40:41], exec
	v_readlane_b32 s8, v254, 3
	v_readlane_b32 s9, v254, 4
	s_and_b64 s[8:9], s[40:41], s[8:9]
	s_mov_b64 exec, s[8:9]
	s_cbranch_execz .LBB0_771
	buffer_inv sc1
	v_readlane_b32 s20, v254, 61
	v_readlane_b32 s21, v254, 62
	v_readlane_b32 s6, v255, 60
	v_mov_b32_e32 v0, 1
	s_nop 3
	s_add_i32 s6, s6, 32
	global_atomic_add v49, v0, s[20:21]
	v_writelane_b32 v255, s6, 60
.Llb_poll2:
	global_load_dword v1, v49, s[20:21] sc1
	s_waitcnt vmcnt(0)
	v_readfirstlane_b32 s9, v1
	s_nop 0
	s_cmp_ge_u32 s9, s6
	s_cbranch_scc1 .Llb_done2
	s_sleep 1
	s_branch .Llb_poll2
.Llb_done2:
.LBB0_771:
	s_or_b64 exec, exec, s[40:41]
	s_barrier

.LBB0_1008:
	s_and_b64 vcc, exec, s[40:41]
	s_cbranch_vccz .LBB0_1028
	s_waitcnt vmcnt(0)
	s_barrier
	s_mov_b64 s[40:41], exec
	v_readlane_b32 s6, v254, 3
	v_readlane_b32 s7, v254, 4
	s_and_b64 s[6:7], s[40:41], s[6:7]
	s_mov_b64 exec, s[6:7]
	s_cbranch_execz .LBB0_1027
	buffer_inv sc1
	v_readlane_b32 s20, v254, 61
	v_readlane_b32 s21, v254, 62
	v_readlane_b32 s6, v255, 60
	v_mov_b32_e32 v0, 1
	s_nop 3
	s_add_i32 s6, s6, 32
	global_atomic_add v49, v0, s[20:21]
	v_writelane_b32 v255, s6, 60

.LBB0_1175:
	s_and_b64 vcc, exec, s[38:39]
	v_readlane_b32 s73, v255, 21
	s_cbranch_vccz .LBB0_1195
	s_waitcnt vmcnt(0)
	s_barrier
	s_mov_b64 s[38:39], exec
	v_readlane_b32 s6, v254, 3
	v_readlane_b32 s7, v254, 4
	s_and_b64 s[6:7], s[38:39], s[6:7]
	s_mov_b64 exec, s[6:7]
	s_cbranch_execz .LBB0_1194
	buffer_inv sc1
	v_readlane_b32 s20, v254, 61
	v_readlane_b32 s21, v254, 62
	v_readlane_b32 s6, v255, 60
	v_mov_b32_e32 v0, 1
	s_nop 3
	s_add_i32 s6, s6, 32
	global_atomic_add v49, v0, s[20:21]
	v_writelane_b32 v255, s6, 60

.LBB0_1259:
	s_and_b64 vcc, exec, s[2:3]
	s_cbranch_vccz .LBB0_1279
	s_waitcnt vmcnt(0)
	s_barrier
	s_mov_b64 s[2:3], exec
	v_readlane_b32 s6, v254, 3
	v_readlane_b32 s7, v254, 4
	s_and_b64 s[6:7], s[2:3], s[6:7]
	s_mov_b64 exec, s[6:7]
	s_cbranch_execz .LBB0_1278
	buffer_inv sc1
	v_readlane_b32 s20, v254, 61
	v_readlane_b32 s21, v254, 62
	v_readlane_b32 s6, v255, 60
	v_mov_b32_e32 v0, 1
	s_nop 3
	s_add_i32 s6, s6, 32
	global_atomic_add v49, v0, s[20:21]
	v_writelane_b32 v255, s6, 60

.Llb_done5:
.LBB0_1278:
	s_or_b64 exec, exec, s[2:3]
	s_barrier

.LBB0_1379:
	s_and_b64 vcc, exec, s[2:3]
	s_cbranch_vccz .LBB0_1399
	s_waitcnt vmcnt(0)
	s_barrier
	s_mov_b64 s[2:3], exec
	v_readlane_b32 s8, v254, 3
	v_readlane_b32 s9, v254, 4
	s_and_b64 s[8:9], s[2:3], s[8:9]
	s_mov_b64 exec, s[8:9]
	s_cbranch_execz .LBB0_1398
	buffer_inv sc1
	v_readlane_b32 s20, v254, 61
	v_readlane_b32 s21, v254, 62
	v_readlane_b32 s6, v255, 60
	v_mov_b32_e32 v0, 1
	s_nop 3
	s_add_i32 s6, s6, 32
	global_atomic_add v49, v0, s[20:21]
	v_writelane_b32 v255, s6, 60
